# first arriver of each XCD starts an early non-blocking L2 writeback at the grid barrier
# baseline (speedup 1.0000x reference)
.Lgb_q2_s0:
	s_cmp_lg_u32 s16, 0
	s_cbranch_scc1 .Lgb_ne_s0
	buffer_wbl2 sc1

.Lgb_spin_s0:
	global_load_dword v7, v0, s[6:7] sc1
	s_add_u32 s18, s18, 1
	s_waitcnt vmcnt(0)
	v_sub_u32_e32 v7, v7, v6
	v_cmp_lt_i32_e32 vcc, -1, v7
	s_nop 1
	s_bcnt1_i32_b64 s17, vcc
	s_cmp_ge_u32 s17, s13
	s_cbranch_scc1 .Lgb_acq_s0
	s_sleep 1
	s_cmp_lt_u32 s18, 0x40000
	s_cbranch_scc1 .Lgb_spin_s0

.Lgb_q2_s1:
	s_cmp_lg_u32 s18, 0
	s_cbranch_scc1 .Lgb_ne_s1
	buffer_wbl2 sc1

.Lgb_spin_s1:
	global_load_dword v7, v0, s[6:7] sc1
	s_add_u32 s20, s20, 1
	s_waitcnt vmcnt(0)
	v_sub_u32_e32 v7, v7, v6
	v_cmp_lt_i32_e32 vcc, -1, v7
	s_nop 1
	s_bcnt1_i32_b64 s19, vcc
	s_cmp_ge_u32 s19, s13
	s_cbranch_scc1 .Lgb_acq_s1
	s_sleep 1
	s_cmp_lt_u32 s20, 0x40000
	s_cbranch_scc1 .Lgb_spin_s1

.Lgb_q2_s2:
	s_cmp_lg_u32 s14, 0
	s_cbranch_scc1 .Lgb_ne_s2
	buffer_wbl2 sc1

.Lgb_spin_s2:
	global_load_dword v7, v0, s[6:7] sc1
	s_add_u32 s18, s18, 1
	s_waitcnt vmcnt(0)
	v_sub_u32_e32 v7, v7, v6
	v_cmp_lt_i32_e32 vcc, -1, v7
	s_nop 1
	s_bcnt1_i32_b64 s15, vcc
	s_cmp_ge_u32 s15, s11
	s_cbranch_scc1 .Lgb_acq_s2
	s_sleep 1
	s_cmp_lt_u32 s18, 0x40000
	s_cbranch_scc1 .Lgb_spin_s2

.Lgb_q2_s3:
	s_cmp_lg_u32 s12, 0
	s_cbranch_scc1 .Lgb_ne_s3
	buffer_wbl2 sc1

.Lgb_spin_s3:
	global_load_dword v7, v0, s[4:5] sc1
	s_add_u32 s14, s14, 1
	s_waitcnt vmcnt(0)
	v_sub_u32_e32 v7, v7, v6
	v_cmp_lt_i32_e32 vcc, -1, v7
	s_nop 1
	s_bcnt1_i32_b64 s13, vcc
	s_cmp_ge_u32 s13, s9
	s_cbranch_scc1 .Lgb_acq_s3
	s_sleep 1
	s_cmp_lt_u32 s14, 0x40000
	s_cbranch_scc1 .Lgb_spin_s3

.Lgb_q2_s4:
	s_cmp_lg_u32 s11, 0
	s_cbranch_scc1 .Lgb_ne_s4
	buffer_wbl2 sc1

.Lgb_spin_s4:
	global_load_dword v6, v0, s[4:5] sc1
	s_add_u32 s13, s13, 1
	s_waitcnt vmcnt(0)
	v_sub_u32_e32 v6, v6, v3
	v_cmp_lt_i32_e32 vcc, -1, v6
	s_nop 1
	s_bcnt1_i32_b64 s12, vcc
	s_cmp_ge_u32 s12, s8
	s_cbranch_scc1 .Lgb_acq_s4
	s_sleep 1
	s_cmp_lt_u32 s13, 0x40000
	s_cbranch_scc1 .Lgb_spin_s4

.Lgb_spin_s5:
	global_load_dword v7, v0, s[4:5] sc1
	s_add_u32 s13, s13, 1
	s_waitcnt vmcnt(0)
	v_sub_u32_e32 v7, v7, v6
	v_cmp_lt_i32_e32 vcc, -1, v7
	s_nop 1
	s_bcnt1_i32_b64 s12, vcc
	s_cmp_ge_u32 s12, s8
	s_cbranch_scc1 .Lgb_acq_s5
	s_sleep 1
	s_cmp_lt_u32 s13, 0x40000
	s_cbranch_scc1 .Lgb_spin_s5

.Lgb_spin_s6:
	global_load_dword v7, v0, s[4:5] sc1
	s_add_u32 s18, s18, 1
	s_waitcnt vmcnt(0)
	v_sub_u32_e32 v7, v7, v6
	v_cmp_lt_i32_e32 vcc, -1, v7
	s_nop 1
	s_bcnt1_i32_b64 s15, vcc
	s_cmp_ge_u32 s15, s11
	s_cbranch_scc1 .Lgb_acq_s6
	s_sleep 1
	s_cmp_lt_u32 s18, 0x40000
	s_cbranch_scc1 .Lgb_spin_s6
